# NSA pipelining v2: next tile's K fragment reads issued at the step top, first QK MFMAs inside the row-max chain, rest spread over the exp section
# speedup vs baseline: 1.0020x; 1.0009x over previous
.LBB0_743:
	ds_read_b128 v[226:229], v221 offset:16384
	ds_read_b128 v[230:233], v221 offset:20480
	ds_read_b128 v[234:237], v222 offset:16384
	ds_read_b128 v[238:241], v222 offset:20480
	s_cmp_eq_u32 s50, s74
	s_cselect_b64 s[4:5], -1, 0
	s_cmp_lg_u32 s50, s74
	s_cbranch_scc1 .LBB0_745
	v_and_b32_e32 v4, 64, v198
	v_xor_b32_e32 v2, 32, v198
	v_add_u32_e32 v4, 64, v4
	v_cmp_lt_i32_e32 vcc, v2, v4
	v_mov_b32_e32 v16, v3
	v_mov_b32_e32 v17, v3
	v_cndmask_b32_e32 v2, v198, v2, vcc
	v_lshlrev_b32_e32 v2, 2, v2
	ds_bpermute_b32 v2, v2, v214
	v_mov_b32_e32 v9, v3
	v_mov_b32_e32 v10, v3
	v_mov_b32_e32 v11, v3
	v_mov_b32_e32 v12, v3
	s_waitcnt lgkmcnt(0)
	v_add_f32_e32 v2, v214, v2
	v_div_scale_f32 v4, s[8:9], v2, v2, v197
	v_rcp_f32_e32 v5, v4
	v_div_scale_f32 v6, vcc, v197, v2, v197
	v_mov_b32_e32 v13, v3
	v_fma_f32 v7, -v4, v5, 1.0
	v_fmac_f32_e32 v5, v7, v5
	v_mul_f32_e32 v7, v6, v5
	v_fma_f32 v8, -v4, v7, v6
	v_fmac_f32_e32 v7, v8, v5
	v_fma_f32 v4, -v4, v7, v6
	v_div_fmas_f32 v4, v4, v5, v7
	v_div_fixup_f32 v4, v4, v2, v197
	v_cmp_lt_f32_e32 vcc, 0, v2
	v_mov_b32_e32 v5, v3
	v_mov_b32_e32 v6, v3
	v_cndmask_b32_e32 v2, 0, v4, vcc
	v_pk_fma_f32 v[48:49], v[80:81], v[2:3], v[48:49] op_sel_hi:[1,0,1]
	v_pk_fma_f32 v[46:47], v[78:79], v[2:3], v[46:47] op_sel_hi:[1,0,1]
	v_pk_fma_f32 v[44:45], v[76:77], v[2:3], v[44:45] op_sel_hi:[1,0,1]
	v_pk_fma_f32 v[42:43], v[74:75], v[2:3], v[42:43] op_sel_hi:[1,0,1]
	v_pk_fma_f32 v[40:41], v[72:73], v[2:3], v[40:41] op_sel_hi:[1,0,1]
	v_pk_fma_f32 v[38:39], v[70:71], v[2:3], v[38:39] op_sel_hi:[1,0,1]
	v_pk_fma_f32 v[36:37], v[68:69], v[2:3], v[36:37] op_sel_hi:[1,0,1]
	v_pk_fma_f32 v[34:35], v[66:67], v[2:3], v[34:35] op_sel_hi:[1,0,1]
	v_pk_fma_f32 v[32:33], v[64:65], v[2:3], v[32:33] op_sel_hi:[1,0,1]
	v_pk_fma_f32 v[30:31], v[62:63], v[2:3], v[30:31] op_sel_hi:[1,0,1]
	v_pk_fma_f32 v[28:29], v[60:61], v[2:3], v[28:29] op_sel_hi:[1,0,1]
	v_pk_fma_f32 v[26:27], v[58:59], v[2:3], v[26:27] op_sel_hi:[1,0,1]
	v_pk_fma_f32 v[24:25], v[56:57], v[2:3], v[24:25] op_sel_hi:[1,0,1]
	v_pk_fma_f32 v[22:23], v[54:55], v[2:3], v[22:23] op_sel_hi:[1,0,1]
	v_pk_fma_f32 v[20:21], v[52:53], v[2:3], v[20:21] op_sel_hi:[1,0,1]
	v_pk_fma_f32 v[18:19], v[50:51], v[2:3], v[18:19] op_sel_hi:[1,0,1]
	v_mov_b32_e32 v2, v3
	v_mov_b32_e32 v4, v3
	v_mov_b32_e32 v7, v3
	v_mov_b32_e32 v8, v3
	v_mov_b32_e32 v14, v3
	v_mov_b32_e32 v15, v3
	v_mov_b64_e32 v[64:65], v[16:17]
	v_mov_b64_e32 v[80:81], v[16:17]
	v_mov_b32_e32 v216, 0xff800000
	v_mov_b32_e32 v214, 0
	v_mov_b64_e32 v[62:63], v[14:15]
	v_mov_b64_e32 v[60:61], v[12:13]
	v_mov_b64_e32 v[58:59], v[10:11]
	v_mov_b64_e32 v[56:57], v[8:9]
	v_mov_b64_e32 v[54:55], v[6:7]
	v_mov_b64_e32 v[52:53], v[4:5]
	v_mov_b64_e32 v[50:51], v[2:3]
	v_mov_b64_e32 v[78:79], v[14:15]
	v_mov_b64_e32 v[76:77], v[12:13]
	v_mov_b64_e32 v[74:75], v[10:11]
	v_mov_b64_e32 v[72:73], v[8:9]
	v_mov_b64_e32 v[70:71], v[6:7]
	v_mov_b64_e32 v[68:69], v[4:5]
	v_mov_b64_e32 v[66:67], v[2:3]

; #define LAS __attribute__((address_space(3)))
; #define MFMA32(a, b, c) __builtin_amdgcn_mfma_f32_32x32x16_bf16((a), (b), (c), 0, 0, 0)
; DI float fexp2(float x) { return __builtin_amdgcn_exp2f(x); }
; DI float half_max(float v) { return fmaxf(v, __shfl_xor(v, 32)); }
; DI void flash_qk(const LAS unsigned char* kb, const bf16x8 (&qf)[4], f32x16& p0, f32x16& p1, int r32, int h) {
;     ...
;     for (int s = 0; s < 4; ++s) {
;         const int off = r32 * 128 + (((2 * s + h) ^ sw) << 4);
;         const bf16x8 a0 = *(const LAS bf16x8*)(kb + off), a1 = *(const LAS bf16x8*)(kb + off + 4096);
;         p0 = MFMA32(a0, qf[s], p0); p1 = MFMA32(a1, qf[s], p1);
;     }
; DI void flash_pv(FState& st, f32x16& p0, f32x16& p1, bool rowon, const LAS unsigned char* vb, int lane) {
;     float mx = fmaxf(p0[0], p1[0]);
; #pragma unroll
;     for (int r = 1; r < 16; ++r) asm("v_max3_f32 %0, %1, %2, %3" : "=v"(mx) : "v"(mx), "v"(p0[r]), "v"(p1[r]));
;     mx = half_max(mx);
;     mx = rowon ? mx : NINF;
;     const bool upd = mx > st.m + THR_RAW;
;     if (__any(upd)) {
;         const float mn = upd ? mx : st.m;
;         const float alpha = upd ? fexp2((st.m - mn) * SM_C) : 1.0f;
;         st.m = mn; st.l *= alpha;
; #pragma unroll
;         for (int r = 0; r < 16; ++r) { st.o0[r] *= alpha; st.o1[r] *= alpha; }
;     }
.LBB0_753:
	v_max_f32_e32 v2, v82, v82
	v_max_f32_e32 v4, v98, v98
	v_max_f32_e32 v2, v4, v2
	v_max3_f32 v2, v2, v99, v83
	s_waitcnt lgkmcnt(3)
	v_mfma_f32_32x32x16_bf16 v[130:145], v[226:229], v[146:149], 0
	v_and_b32_e32 v5, 64, v198
	v_max3_f32 v2, v2, v100, v84
	v_xor_b32_e32 v4, 32, v198
	v_max3_f32 v2, v2, v101, v85
	v_add_u32_e32 v5, 64, v5
	s_waitcnt lgkmcnt(2)
	v_mfma_f32_32x32x16_bf16 v[114:129], v[230:233], v[146:149], 0
	ds_read_b128 v[226:229], v223 offset:16384
	ds_read_b128 v[230:233], v223 offset:20480
	v_max3_f32 v2, v2, v102, v86
	v_cmp_lt_i32_e32 vcc, v4, v5
	v_max3_f32 v2, v2, v103, v87
	v_max3_f32 v2, v2, v104, v88
	v_max3_f32 v2, v2, v105, v89
	s_waitcnt lgkmcnt(3)
	v_mfma_f32_32x32x16_bf16 v[130:145], v[234:237], v[150:153], v[130:145]
	v_cndmask_b32_e32 v4, v198, v4, vcc
	v_max3_f32 v2, v2, v106, v90
	v_lshlrev_b32_e32 v215, 2, v4
	v_max3_f32 v2, v2, v107, v91
	v_max3_f32 v2, v2, v108, v92
	v_max3_f32 v2, v2, v109, v93
	v_max3_f32 v2, v2, v110, v94
	v_max3_f32 v2, v2, v111, v95
	v_max3_f32 v2, v2, v112, v96
	v_max3_f32 v2, v2, v113, v97
	v_mov_b32_e32 v4, v2
	s_nop 1
	v_permlane32_swap_b32_e32 v4, v2
	s_nop 0
	v_max_f32_e32 v2, v2, v4
	v_cndmask_b32_e64 v2, v186, v2, s[8:9]
	v_add_f32_e32 v4, 0x42317218, v216
	v_cmp_gt_f32_e32 vcc, v2, v4
	s_cbranch_vccz .LBB0_755
	s_nop 0
	v_cndmask_b32_e32 v4, v216, v2, vcc
	v_sub_f32_e32 v2, v216, v4
	v_mul_f32_e32 v2, 0x3e38aa3b, v2
	v_exp_f32_e32 v2, v2
	v_mov_b32_e32 v216, v4
	v_cndmask_b32_e32 v2, 1.0, v2, vcc
	v_mul_f32_e32 v214, v214, v2
	v_pk_mul_f32 v[80:81], v[80:81], v[2:3] op_sel_hi:[1,0]
	v_pk_mul_f32 v[78:79], v[78:79], v[2:3] op_sel_hi:[1,0]
	v_pk_mul_f32 v[76:77], v[76:77], v[2:3] op_sel_hi:[1,0]
	v_pk_mul_f32 v[74:75], v[74:75], v[2:3] op_sel_hi:[1,0]
	v_pk_mul_f32 v[72:73], v[72:73], v[2:3] op_sel_hi:[1,0]
	v_pk_mul_f32 v[70:71], v[70:71], v[2:3] op_sel_hi:[1,0]
	v_pk_mul_f32 v[68:69], v[68:69], v[2:3] op_sel_hi:[1,0]
	v_pk_mul_f32 v[66:67], v[66:67], v[2:3] op_sel_hi:[1,0]
	v_pk_mul_f32 v[64:65], v[64:65], v[2:3] op_sel_hi:[1,0]
	v_pk_mul_f32 v[62:63], v[62:63], v[2:3] op_sel_hi:[1,0]
	v_pk_mul_f32 v[60:61], v[60:61], v[2:3] op_sel_hi:[1,0]
	v_pk_mul_f32 v[58:59], v[58:59], v[2:3] op_sel_hi:[1,0]
	v_pk_mul_f32 v[56:57], v[56:57], v[2:3] op_sel_hi:[1,0]
	v_pk_mul_f32 v[54:55], v[54:55], v[2:3] op_sel_hi:[1,0]
	v_pk_mul_f32 v[52:53], v[52:53], v[2:3] op_sel_hi:[1,0]
	v_pk_mul_f32 v[50:51], v[50:51], v[2:3] op_sel_hi:[1,0]

; #define LAS __attribute__((address_space(3)))
; #define MFMA32(a, b, c) __builtin_amdgcn_mfma_f32_32x32x16_bf16((a), (b), (c), 0, 0, 0)
; DI float fexp2(float x) { return __builtin_amdgcn_exp2f(x); }
; DI s16x4 vtr(const LAS unsigned char* p) { return __builtin_bit_cast(s16x4, __builtin_amdgcn_ds_read_tr16_b64_v4i16((LAS v4i16_t*)p)); }
; DI void flash_qk(const LAS unsigned char* kb, const bf16x8 (&qf)[4], f32x16& p0, f32x16& p1, int r32, int h) {
;     ...
;     for (int s = 0; s < 4; ++s) {
;         const int off = r32 * 128 + (((2 * s + h) ^ sw) << 4);
;         const bf16x8 a0 = *(const LAS bf16x8*)(kb + off), a1 = *(const LAS bf16x8*)(kb + off + 4096);
;         p0 = MFMA32(a0, qf[s], p0); p1 = MFMA32(a1, qf[s], p1);
;     }
; DI void flash_pv(FState& st, f32x16& p0, f32x16& p1, bool rowon, const LAS unsigned char* vb, int lane) {
;     ...
;     const float cl = rowon ? SM_C : 0.0f;
;     const float bl = rowon ? ((st.m == NINF) ? 0.0f : -st.m * SM_C) : NINF;
;     float sum = 0.f;
; #pragma unroll
;     for (int r = 0; r < 16; ++r) { p0[r] = fexp2(__builtin_fmaf(p0[r], cl, bl)); p1[r] = fexp2(__builtin_fmaf(p1[r], cl, bl)); sum += p0[r] + p1[r]; }
;     st.l += sum;
;     const int h = lane >> 5;
;     const int vx = (((lane & 15) >> 3) & 1) * 64;
;     const LAS unsigned char* vp = vb + (4 * h + ((lane & 15) >> 2)) * 128 + ((lane >> 4) & 1) * 32 + (lane & 3) * 8;
; #pragma unroll
;     for (int sub = 0; sub < 2; ++sub)
; #pragma unroll
;         for (int s2 = 0; s2 < 2; ++s2) {
;             const bf16x8 pf = pack8h(sub ? p1 : p0, s2);
;             const LAS unsigned char* vq = vp + (32 * sub + 16 * s2) * 128;
;             { const s16x4 lo = vtr(vq + vx), hi = vtr(vq + 1024 + vx); const bf16x8 vf = {lo[0], lo[1], lo[2], lo[3], hi[0], hi[1], hi[2], hi[3]}; st.o0 = MFMA32(vf, pf, st.o0); }
;             { const s16x4 lo = vtr(vq + (64 - vx)), hi = vtr(vq + 1024 + (64 - vx)); const bf16x8 vf = {lo[0], lo[1], lo[2], lo[3], hi[0], hi[1], hi[2], hi[3]}; st.o1 = MFMA32(vf, pf, st.o1); }
.LBB0_759:
	s_or_b64 exec, exec, s[4:5]
	s_waitcnt lgkmcnt(2)
	v_mfma_f32_32x32x16_bf16 v[114:129], v[238:241], v[150:153], v[114:129]
	ds_read_b128 v[234:237], v224 offset:16384
	ds_read_b128 v[238:241], v224 offset:20480
	v_fma_f32 v2, v98, v5, v4
	v_exp_f32_e32 v12, v2
	v_fma_f32 v2, v82, v5, v4
	v_exp_f32_e32 v246, v2
	v_fma_f32 v2, v99, v5, v4
	v_exp_f32_e32 v6, v2
	v_fma_f32 v2, v83, v5, v4
	v_exp_f32_e32 v2, v2
	v_add_f32_e32 v7, v12, v246
	s_add_i32 s77, s74, 1
	s_waitcnt lgkmcnt(3)
	v_mfma_f32_32x32x16_bf16 v[130:145], v[226:229], v[154:157], v[130:145]
	s_cmp_ge_u32 s77, s51
	v_pk_add_f32 v[8:9], v[6:7], v[2:3]
	v_fma_f32 v7, v100, v5, v4
	v_pk_add_f32 v[98:99], v[8:9], v[8:9] op_sel_hi:[0,1]
	v_fma_f32 v8, v84, v5, v4
	v_exp_f32_e32 v7, v7
	v_exp_f32_e32 v247, v8
	v_fma_f32 v8, v101, v5, v4
	v_fma_f32 v9, v85, v5, v4
	v_exp_f32_e32 v8, v8
	s_waitcnt lgkmcnt(2)
	v_mfma_f32_32x32x16_bf16 v[114:129], v[230:233], v[154:157], v[114:129]
	v_exp_f32_e32 v98, v9
	v_add_f32_e32 v9, v7, v247
	v_cvt_pk_bf16_f32 v6, v12, v6
	v_cvt_pk_bf16_f32 v7, v7, v8
	v_pk_add_f32 v[10:11], v[8:9], v[98:99]
	v_fma_f32 v9, v102, v5, v4
	v_pk_add_f32 v[100:101], v[10:11], v[10:11] op_sel_hi:[0,1]
	v_fma_f32 v10, v86, v5, v4
	v_exp_f32_e32 v99, v10
	v_fma_f32 v10, v103, v5, v4
	s_waitcnt lgkmcnt(1)
	v_mfma_f32_32x32x16_bf16 v[130:145], v[234:237], v[158:161], v[130:145]
	v_exp_f32_e32 v9, v9
	v_exp_f32_e32 v14, v10
	v_fma_f32 v10, v87, v5, v4
	v_exp_f32_e32 v100, v10
	v_add_f32_e32 v15, v9, v99
	v_cvt_pk_bf16_f32 v8, v9, v14
	v_pk_add_f32 v[10:11], v[14:15], v[100:101]
	s_nop 0
	v_pk_add_f32 v[86:87], v[10:11], v[10:11] op_sel_hi:[0,1]
	v_fma_f32 v10, v104, v5, v4
	s_waitcnt lgkmcnt(0)
	v_mfma_f32_32x32x16_bf16 v[114:129], v[238:241], v[158:161], v[114:129]
	v_exp_f32_e32 v15, v10
	v_fma_f32 v10, v88, v5, v4
	v_exp_f32_e32 v101, v10
	v_fma_f32 v10, v105, v5, v4
	v_exp_f32_e32 v16, v10
	v_fma_f32 v10, v89, v5, v4
	v_exp_f32_e32 v86, v10
	v_add_f32_e32 v17, v15, v101
	v_cvt_pk_bf16_f32 v9, v15, v16
	v_pk_add_f32 v[10:11], v[16:17], v[86:87]
	s_nop 0
	v_pk_add_f32 v[88:89], v[10:11], v[10:11] op_sel_hi:[0,1]
	v_fma_f32 v10, v106, v5, v4
	v_exp_f32_e32 v87, v10
	v_fma_f32 v10, v90, v5, v4
	v_exp_f32_e32 v248, v10
	v_fma_f32 v10, v107, v5, v4
	v_exp_f32_e32 v90, v10
	v_fma_f32 v10, v91, v5, v4
	v_exp_f32_e32 v88, v10
	v_fma_f32 v10, v108, v5, v4
	v_exp_f32_e32 v107, v10
	v_fma_f32 v10, v92, v5, v4
	v_add_f32_e32 v91, v87, v248
	v_exp_f32_e32 v108, v10
	v_pk_add_f32 v[10:11], v[90:91], v[88:89]
	v_fma_f32 v91, v112, v5, v4
	v_pk_add_f32 v[102:103], v[10:11], v[10:11] op_sel_hi:[0,1]
	v_fma_f32 v10, v109, v5, v4
	v_exp_f32_e32 v104, v10
	v_fma_f32 v10, v93, v5, v4
	v_exp_f32_e32 v102, v10
	v_add_u32_e32 v10, s76, v211
	v_add3_u32 v17, v10, v203, v204
	v_add_u32_e32 v218, v17, v202
	ds_read_b64_tr_b16 v[10:11], v218 offset:8192
	ds_read_b64_tr_b16 v[12:13], v218 offset:9216
	v_add_u32_e32 v217, v17, v213
	ds_read_b64_tr_b16 v[14:15], v217 offset:8256
	ds_read_b64_tr_b16 v[16:17], v217 offset:9280
	ds_read_b64_tr_b16 v[82:83], v218 offset:10240
	ds_read_b64_tr_b16 v[84:85], v218 offset:11264
	s_waitcnt lgkmcnt(4)
	v_mfma_f32_32x32x16_bf16 v[66:81], v[10:13], v[6:9], v[66:81]
	v_fma_f32 v10, v110, v5, v4
	v_exp_f32_e32 v89, v10
	v_fma_f32 v10, v111, v5, v4
	v_exp_f32_e32 v92, v10
	v_exp_f32_e32 v109, v91
	v_add_f32_e32 v105, v107, v108
	ds_read_b64_tr_b16 v[10:11], v217 offset:10304
	ds_read_b64_tr_b16 v[12:13], v217 offset:11328
	s_waitcnt lgkmcnt(4)
	v_mfma_f32_32x32x16_bf16 v[50:65], v[14:17], v[6:9], v[50:65]
	v_fma_f32 v6, v113, v5, v4
	v_exp_f32_e32 v106, v6
	v_cvt_pk_bf16_f32 v6, v87, v90
	v_cvt_pk_bf16_f32 v7, v107, v104
	v_cvt_pk_bf16_f32 v8, v89, v92
	v_cvt_pk_bf16_f32 v9, v109, v106
	v_pk_add_f32 v[14:15], v[104:105], v[102:103]
	s_waitcnt lgkmcnt(2)
	v_mfma_f32_32x32x16_bf16 v[66:81], v[82:85], v[6:9], v[66:81]
	v_add_f32_e64 v90, v14, v14
	v_add_f32_e64 v91, v14, v15
	v_fma_f32 v14, v94, v5, v4
	v_exp_f32_e32 v94, v14
	ds_read_b64_tr_b16 v[14:15], v218 offset:12288
	ds_read_b64_tr_b16 v[16:17], v218 offset:13312
	v_fma_f32 v82, v95, v5, v4
	v_exp_f32_e32 v90, v82
	v_add_f32_e32 v93, v89, v94
	s_waitcnt lgkmcnt(2)
	v_mfma_f32_32x32x16_bf16 v[50:65], v[10:13], v[6:9], v[50:65]
	v_cvt_pk_bf16_f32 v6, v246, v2
	v_cvt_pk_bf16_f32 v7, v247, v98
	v_cvt_pk_bf16_f32 v8, v99, v100
	v_cvt_pk_bf16_f32 v9, v101, v86
	ds_read_b64_tr_b16 v[10:11], v218 offset:14336
	ds_read_b64_tr_b16 v[12:13], v218 offset:15360
	v_pk_add_f32 v[82:83], v[92:93], v[90:91]
	v_fma_f32 v2, v96, v5, v4
	s_waitcnt lgkmcnt(2)
	v_mfma_f32_32x32x16_bf16 v[66:81], v[14:17], v[6:9], v[66:81]
	ds_read_b64_tr_b16 v[14:15], v217 offset:12352
	ds_read_b64_tr_b16 v[16:17], v217 offset:13376
	v_add_f32_e64 v86, v82, v82
	v_add_f32_e64 v87, v82, v83
	v_fmac_f32_e32 v4, v97, v5
	ds_read_b64_tr_b16 v[82:83], v217 offset:14400
	ds_read_b64_tr_b16 v[84:85], v217 offset:15424
	v_exp_f32_e32 v2, v2
	v_exp_f32_e32 v86, v4
	v_cvt_pk_bf16_f32 v4, v248, v88
	s_waitcnt lgkmcnt(2)
	v_mfma_f32_32x32x16_bf16 v[50:65], v[14:17], v[6:9], v[50:65]
	v_cvt_pk_bf16_f32 v5, v108, v102
	v_cvt_pk_bf16_f32 v6, v94, v90
	v_cvt_pk_bf16_f32 v7, v2, v86
	v_add_f32_e32 v107, v109, v2
	v_add_f32_e64 v8, v106, v86
	v_add_f32_e64 v9, v107, v87
	v_add_f32_e32 v2, v8, v9
	v_mfma_f32_32x32x16_bf16 v[66:81], v[10:13], v[4:7], v[66:81]
	v_add_f32_e32 v214, v214, v2
	s_waitcnt lgkmcnt(0)
	v_mfma_f32_32x32x16_bf16 v[50:65], v[82:85], v[4:7], v[50:65]
	s_cbranch_scc1 .LBB0_780
	s_movk_i32 s76, 0x4000
	s_add_i32 s4, s74, 5
	s_cmp_ge_u32 s4, s51
	s_waitcnt vmcnt(1)
	ds_write_b128 v205, v[182:185] offset:32768
	s_waitcnt vmcnt(0)
	ds_write_b128 v212, v[178:181] offset:40960
	s_waitcnt lgkmcnt(0)
	s_barrier
	s_cbranch_scc1 .LBB0_762
	s_cmp_gt_u32 s4, s69
	s_cselect_b64 s[8:9], -1, 0
	s_mov_b32 s5, s52
	s_and_b64 s[8:9], s[8:9], exec
	s_cselect_b32 s4, s5, s4
	s_cselect_b32 s16, 0x1000, s65
	s_cselect_b32 s8, s64, 0x500
	s_lshl_b32 s4, s4, 6
	s_mov_b32 s9, s17
	v_mad_i64_i32 v[4:5], s[4:5], s4, v199, v[192:193]
	v_lshl_add_u64 v[6:7], v[4:5], 0, s[8:9]
	v_lshl_add_u64 v[4:5], v[4:5], 0, s[16:17]
	global_load_dwordx4 v[182:185], v[6:7], off
	global_load_dwordx4 v[178:181], v[4:5], off
.LBB0_762:
	ds_read_b128 v[226:229], v221 offset:32768
	ds_read_b128 v[230:233], v221 offset:36864
	ds_read_b128 v[234:237], v222 offset:32768
	ds_read_b128 v[238:241], v222 offset:36864
	s_cmp_eq_u32 s69, s74
	s_cselect_b64 s[4:5], -1, 0
	s_cmp_lg_u32 s69, s74
	s_cbranch_scc1 .LBB0_764
	ds_bpermute_b32 v2, v215, v214
	v_mov_b32_e32 v16, v3
	v_mov_b32_e32 v17, v3
	v_mov_b32_e32 v9, v3
	v_mov_b32_e32 v10, v3
	s_waitcnt lgkmcnt(0)
	v_add_f32_e32 v2, v214, v2
	v_div_scale_f32 v4, s[8:9], v2, v2, v197
	v_rcp_f32_e32 v5, v4
	v_div_scale_f32 v6, vcc, v197, v2, v197
	v_mov_b32_e32 v11, v3
	v_fma_f32 v7, -v4, v5, 1.0
	v_fmac_f32_e32 v5, v7, v5
	v_mul_f32_e32 v7, v6, v5
	v_fma_f32 v8, -v4, v7, v6
	v_fmac_f32_e32 v7, v8, v5
	v_fma_f32 v4, -v4, v7, v6
	v_div_fmas_f32 v4, v4, v5, v7
	v_div_fixup_f32 v4, v4, v2, v197
	v_cmp_lt_f32_e32 vcc, 0, v2
	v_mov_b32_e32 v5, v3
	v_mov_b32_e32 v6, v3
	v_cndmask_b32_e32 v2, 0, v4, vcc
	v_pk_fma_f32 v[48:49], v[80:81], v[2:3], v[48:49] op_sel_hi:[1,0,1]
	v_pk_fma_f32 v[46:47], v[78:79], v[2:3], v[46:47] op_sel_hi:[1,0,1]
	v_pk_fma_f32 v[44:45], v[76:77], v[2:3], v[44:45] op_sel_hi:[1,0,1]
	v_pk_fma_f32 v[42:43], v[74:75], v[2:3], v[42:43] op_sel_hi:[1,0,1]
	v_pk_fma_f32 v[40:41], v[72:73], v[2:3], v[40:41] op_sel_hi:[1,0,1]
	v_pk_fma_f32 v[38:39], v[70:71], v[2:3], v[38:39] op_sel_hi:[1,0,1]
	v_pk_fma_f32 v[36:37], v[68:69], v[2:3], v[36:37] op_sel_hi:[1,0,1]
	v_pk_fma_f32 v[34:35], v[66:67], v[2:3], v[34:35] op_sel_hi:[1,0,1]
	v_pk_fma_f32 v[32:33], v[64:65], v[2:3], v[32:33] op_sel_hi:[1,0,1]
	v_pk_fma_f32 v[30:31], v[62:63], v[2:3], v[30:31] op_sel_hi:[1,0,1]
	v_pk_fma_f32 v[28:29], v[60:61], v[2:3], v[28:29] op_sel_hi:[1,0,1]
	v_pk_fma_f32 v[26:27], v[58:59], v[2:3], v[26:27] op_sel_hi:[1,0,1]
	v_pk_fma_f32 v[24:25], v[56:57], v[2:3], v[24:25] op_sel_hi:[1,0,1]
	v_pk_fma_f32 v[22:23], v[54:55], v[2:3], v[22:23] op_sel_hi:[1,0,1]
	v_pk_fma_f32 v[20:21], v[52:53], v[2:3], v[20:21] op_sel_hi:[1,0,1]
	v_pk_fma_f32 v[18:19], v[50:51], v[2:3], v[18:19] op_sel_hi:[1,0,1]
	v_mov_b32_e32 v2, v3
	v_mov_b32_e32 v4, v3
	v_mov_b32_e32 v7, v3
	v_mov_b32_e32 v8, v3
	v_mov_b32_e32 v12, v3
	v_mov_b32_e32 v13, v3
	v_mov_b32_e32 v14, v3
	v_mov_b32_e32 v15, v3
	v_mov_b64_e32 v[64:65], v[16:17]
	v_mov_b64_e32 v[80:81], v[16:17]
	v_mov_b32_e32 v216, 0xff800000
	v_mov_b32_e32 v214, 0
	v_mov_b64_e32 v[62:63], v[14:15]
	v_mov_b64_e32 v[60:61], v[12:13]
	v_mov_b64_e32 v[58:59], v[10:11]
	v_mov_b64_e32 v[56:57], v[8:9]
	v_mov_b64_e32 v[54:55], v[6:7]
	v_mov_b64_e32 v[52:53], v[4:5]
	v_mov_b64_e32 v[50:51], v[2:3]
	v_mov_b64_e32 v[78:79], v[14:15]
	v_mov_b64_e32 v[76:77], v[12:13]
	v_mov_b64_e32 v[74:75], v[10:11]
	v_mov_b64_e32 v[72:73], v[8:9]
	v_mov_b64_e32 v[70:71], v[6:7]
	v_mov_b64_e32 v[68:69], v[4:5]
	v_mov_b64_e32 v[66:67], v[2:3]

; #define LAS __attribute__((address_space(3)))
; #define MFMA32(a, b, c) __builtin_amdgcn_mfma_f32_32x32x16_bf16((a), (b), (c), 0, 0, 0)
; DI float fexp2(float x) { return __builtin_amdgcn_exp2f(x); }
; DI float half_max(float v) { return fmaxf(v, __shfl_xor(v, 32)); }
; DI void flash_qk(const LAS unsigned char* kb, const bf16x8 (&qf)[4], f32x16& p0, f32x16& p1, int r32, int h) {
;     ...
;     for (int s = 0; s < 4; ++s) {
;         const int off = r32 * 128 + (((2 * s + h) ^ sw) << 4);
;         const bf16x8 a0 = *(const LAS bf16x8*)(kb + off), a1 = *(const LAS bf16x8*)(kb + off + 4096);
;         p0 = MFMA32(a0, qf[s], p0); p1 = MFMA32(a1, qf[s], p1);
;     }
; DI void flash_pv(FState& st, f32x16& p0, f32x16& p1, bool rowon, const LAS unsigned char* vb, int lane) {
;     float mx = fmaxf(p0[0], p1[0]);
; #pragma unroll
;     for (int r = 1; r < 16; ++r) asm("v_max3_f32 %0, %1, %2, %3" : "=v"(mx) : "v"(mx), "v"(p0[r]), "v"(p1[r]));
;     mx = half_max(mx);
;     mx = rowon ? mx : NINF;
;     const bool upd = mx > st.m + THR_RAW;
;     if (__any(upd)) {
;         const float mn = upd ? mx : st.m;
;         const float alpha = upd ? fexp2((st.m - mn) * SM_C) : 1.0f;
;         st.m = mn; st.l *= alpha;
; #pragma unroll
;         for (int r = 0; r < 16; ++r) { st.o0[r] *= alpha; st.o1[r] *= alpha; }
;     }
.LBB0_772:
	v_max_f32_e32 v2, v82, v82
	v_max_f32_e32 v4, v98, v98
	v_max_f32_e32 v2, v4, v2
	v_max3_f32 v2, v2, v99, v83
	s_waitcnt lgkmcnt(3)
	v_mfma_f32_32x32x16_bf16 v[130:145], v[226:229], v[146:149], 0
	v_max3_f32 v2, v2, v100, v84
	v_max3_f32 v2, v2, v101, v85
	v_max3_f32 v2, v2, v102, v86
	v_max3_f32 v2, v2, v103, v87
	v_max3_f32 v2, v2, v104, v88
	s_waitcnt lgkmcnt(2)
	v_mfma_f32_32x32x16_bf16 v[114:129], v[230:233], v[146:149], 0
	ds_read_b128 v[226:229], v223 offset:32768
	ds_read_b128 v[230:233], v223 offset:36864
	v_max3_f32 v2, v2, v105, v89
	v_max3_f32 v2, v2, v106, v90
	v_max3_f32 v2, v2, v107, v91
	v_max3_f32 v2, v2, v108, v92
	v_max3_f32 v2, v2, v109, v93
	s_waitcnt lgkmcnt(3)
	v_mfma_f32_32x32x16_bf16 v[130:145], v[234:237], v[150:153], v[130:145]
	v_max3_f32 v2, v2, v110, v94
	v_max3_f32 v2, v2, v111, v95
	v_max3_f32 v2, v2, v112, v96
	v_max3_f32 v2, v2, v113, v97
	v_mov_b32_e32 v4, v2
	s_nop 1
	v_permlane32_swap_b32_e32 v4, v2
	s_nop 0
	v_max_f32_e32 v2, v2, v4
	v_cndmask_b32_e64 v2, v186, v2, s[8:9]
	v_add_f32_e32 v4, 0x42317218, v216
	v_cmp_gt_f32_e32 vcc, v2, v4
	s_cbranch_vccz .LBB0_774
	s_nop 0
	v_cndmask_b32_e32 v4, v216, v2, vcc
	v_sub_f32_e32 v2, v216, v4
	v_mul_f32_e32 v2, 0x3e38aa3b, v2
	v_exp_f32_e32 v2, v2
	v_mov_b32_e32 v216, v4
	v_cndmask_b32_e32 v2, 1.0, v2, vcc
	v_mul_f32_e32 v214, v214, v2
	v_pk_mul_f32 v[80:81], v[80:81], v[2:3] op_sel_hi:[1,0]
	v_pk_mul_f32 v[78:79], v[78:79], v[2:3] op_sel_hi:[1,0]
	v_pk_mul_f32 v[76:77], v[76:77], v[2:3] op_sel_hi:[1,0]
	v_pk_mul_f32 v[74:75], v[74:75], v[2:3] op_sel_hi:[1,0]
	v_pk_mul_f32 v[72:73], v[72:73], v[2:3] op_sel_hi:[1,0]
	v_pk_mul_f32 v[70:71], v[70:71], v[2:3] op_sel_hi:[1,0]
	v_pk_mul_f32 v[68:69], v[68:69], v[2:3] op_sel_hi:[1,0]
	v_pk_mul_f32 v[66:67], v[66:67], v[2:3] op_sel_hi:[1,0]
	v_pk_mul_f32 v[64:65], v[64:65], v[2:3] op_sel_hi:[1,0]
	v_pk_mul_f32 v[62:63], v[62:63], v[2:3] op_sel_hi:[1,0]
	v_pk_mul_f32 v[60:61], v[60:61], v[2:3] op_sel_hi:[1,0]
	v_pk_mul_f32 v[58:59], v[58:59], v[2:3] op_sel_hi:[1,0]
	v_pk_mul_f32 v[56:57], v[56:57], v[2:3] op_sel_hi:[1,0]
	v_pk_mul_f32 v[54:55], v[54:55], v[2:3] op_sel_hi:[1,0]
	v_pk_mul_f32 v[52:53], v[52:53], v[2:3] op_sel_hi:[1,0]
	v_pk_mul_f32 v[50:51], v[50:51], v[2:3] op_sel_hi:[1,0]

; #define LAS __attribute__((address_space(3)))
; #define MFMA32(a, b, c) __builtin_amdgcn_mfma_f32_32x32x16_bf16((a), (b), (c), 0, 0, 0)
; DI float fexp2(float x) { return __builtin_amdgcn_exp2f(x); }
; DI s16x4 vtr(const LAS unsigned char* p) { return __builtin_bit_cast(s16x4, __builtin_amdgcn_ds_read_tr16_b64_v4i16((LAS v4i16_t*)p)); }
; DI void flash_qk(const LAS unsigned char* kb, const bf16x8 (&qf)[4], f32x16& p0, f32x16& p1, int r32, int h) {
;     ...
;     for (int s = 0; s < 4; ++s) {
;         const int off = r32 * 128 + (((2 * s + h) ^ sw) << 4);
;         const bf16x8 a0 = *(const LAS bf16x8*)(kb + off), a1 = *(const LAS bf16x8*)(kb + off + 4096);
;         p0 = MFMA32(a0, qf[s], p0); p1 = MFMA32(a1, qf[s], p1);
;     }
; DI void flash_pv(FState& st, f32x16& p0, f32x16& p1, bool rowon, const LAS unsigned char* vb, int lane) {
;     ...
;     const float cl = rowon ? SM_C : 0.0f;
;     const float bl = rowon ? ((st.m == NINF) ? 0.0f : -st.m * SM_C) : NINF;
;     float sum = 0.f;
; #pragma unroll
;     for (int r = 0; r < 16; ++r) { p0[r] = fexp2(__builtin_fmaf(p0[r], cl, bl)); p1[r] = fexp2(__builtin_fmaf(p1[r], cl, bl)); sum += p0[r] + p1[r]; }
;     st.l += sum;
;     const int h = lane >> 5;
;     const int vx = (((lane & 15) >> 3) & 1) * 64;
;     const LAS unsigned char* vp = vb + (4 * h + ((lane & 15) >> 2)) * 128 + ((lane >> 4) & 1) * 32 + (lane & 3) * 8;
; #pragma unroll
;     for (int sub = 0; sub < 2; ++sub)
; #pragma unroll
;         for (int s2 = 0; s2 < 2; ++s2) {
;             const bf16x8 pf = pack8h(sub ? p1 : p0, s2);
;             const LAS unsigned char* vq = vp + (32 * sub + 16 * s2) * 128;
;             { const s16x4 lo = vtr(vq + vx), hi = vtr(vq + 1024 + vx); const bf16x8 vf = {lo[0], lo[1], lo[2], lo[3], hi[0], hi[1], hi[2], hi[3]}; st.o0 = MFMA32(vf, pf, st.o0); }
;             { const s16x4 lo = vtr(vq + (64 - vx)), hi = vtr(vq + 1024 + (64 - vx)); const bf16x8 vf = {lo[0], lo[1], lo[2], lo[3], hi[0], hi[1], hi[2], hi[3]}; st.o1 = MFMA32(vf, pf, st.o1); }
;         }
.LBB0_778:
	s_or_b64 exec, exec, s[4:5]
	s_waitcnt lgkmcnt(2)
	v_mfma_f32_32x32x16_bf16 v[114:129], v[238:241], v[150:153], v[114:129]
	ds_read_b128 v[234:237], v224 offset:32768
	ds_read_b128 v[238:241], v224 offset:36864
	v_fma_f32 v2, v98, v5, v4
	v_exp_f32_e32 v12, v2
	v_fma_f32 v2, v82, v5, v4
	v_exp_f32_e32 v246, v2
	v_fma_f32 v2, v99, v5, v4
	v_exp_f32_e32 v6, v2
	v_fma_f32 v2, v83, v5, v4
	v_exp_f32_e32 v2, v2
	v_add_f32_e32 v7, v12, v246
	v_pk_add_f32 v[8:9], v[6:7], v[2:3]
	s_waitcnt lgkmcnt(3)
	v_mfma_f32_32x32x16_bf16 v[130:145], v[226:229], v[154:157], v[130:145]
	s_nop 0
	v_pk_add_f32 v[98:99], v[8:9], v[8:9] op_sel_hi:[0,1]
	v_fma_f32 v7, v100, v5, v4
	v_fma_f32 v8, v84, v5, v4
	v_exp_f32_e32 v7, v7
	v_exp_f32_e32 v247, v8
	v_fma_f32 v8, v101, v5, v4
	v_fma_f32 v9, v85, v5, v4
	v_exp_f32_e32 v8, v8
	v_exp_f32_e32 v98, v9
	s_waitcnt lgkmcnt(2)
	v_mfma_f32_32x32x16_bf16 v[114:129], v[230:233], v[154:157], v[114:129]
	v_add_f32_e32 v9, v7, v247
	v_cvt_pk_bf16_f32 v6, v12, v6
	v_cvt_pk_bf16_f32 v7, v7, v8
	v_pk_add_f32 v[10:11], v[8:9], v[98:99]
	v_fma_f32 v9, v102, v5, v4
	v_pk_add_f32 v[100:101], v[10:11], v[10:11] op_sel_hi:[0,1]
	v_fma_f32 v10, v86, v5, v4
	v_exp_f32_e32 v99, v10
	v_fma_f32 v10, v103, v5, v4
	v_exp_f32_e32 v9, v9
	s_waitcnt lgkmcnt(1)
	v_mfma_f32_32x32x16_bf16 v[130:145], v[234:237], v[158:161], v[130:145]
	v_exp_f32_e32 v14, v10
	v_fma_f32 v10, v87, v5, v4
	v_exp_f32_e32 v100, v10
	v_add_f32_e32 v15, v9, v99
	v_cvt_pk_bf16_f32 v8, v9, v14
	v_pk_add_f32 v[10:11], v[14:15], v[100:101]
	s_nop 0
	v_pk_add_f32 v[86:87], v[10:11], v[10:11] op_sel_hi:[0,1]
	v_fma_f32 v10, v104, v5, v4
	v_exp_f32_e32 v15, v10
	s_waitcnt lgkmcnt(0)
	v_mfma_f32_32x32x16_bf16 v[114:129], v[238:241], v[158:161], v[114:129]
	v_fma_f32 v10, v88, v5, v4
	v_exp_f32_e32 v101, v10
	v_fma_f32 v10, v105, v5, v4
	v_exp_f32_e32 v16, v10
	v_fma_f32 v10, v89, v5, v4
	v_exp_f32_e32 v86, v10
	v_add_f32_e32 v17, v15, v101
	v_cvt_pk_bf16_f32 v9, v15, v16
	v_pk_add_f32 v[10:11], v[16:17], v[86:87]
	s_nop 0
	v_pk_add_f32 v[88:89], v[10:11], v[10:11] op_sel_hi:[0,1]
	v_fma_f32 v10, v106, v5, v4
	v_exp_f32_e32 v87, v10
	v_fma_f32 v10, v90, v5, v4
	v_exp_f32_e32 v248, v10
	v_fma_f32 v10, v107, v5, v4
	v_exp_f32_e32 v90, v10
	v_fma_f32 v10, v91, v5, v4
	v_exp_f32_e32 v88, v10
	v_fma_f32 v10, v108, v5, v4
	v_exp_f32_e32 v107, v10
	v_fma_f32 v10, v92, v5, v4
	v_add_f32_e32 v91, v87, v248
	v_exp_f32_e32 v108, v10
	v_pk_add_f32 v[10:11], v[90:91], v[88:89]
	v_fma_f32 v91, v112, v5, v4
	v_pk_add_f32 v[102:103], v[10:11], v[10:11] op_sel_hi:[0,1]
	v_fma_f32 v10, v109, v5, v4
	v_exp_f32_e32 v104, v10
	v_fma_f32 v10, v93, v5, v4
	v_exp_f32_e32 v102, v10
	v_add_u32_e32 v10, s76, v211
	v_add3_u32 v17, v10, v203, v204
	v_add_u32_e32 v89, v17, v202
	ds_read_b64_tr_b16 v[10:11], v89 offset:8192
	ds_read_b64_tr_b16 v[12:13], v89 offset:9216
	v_add_u32_e32 v109, v17, v213
	ds_read_b64_tr_b16 v[14:15], v109 offset:8256
	ds_read_b64_tr_b16 v[16:17], v109 offset:9280
	ds_read_b64_tr_b16 v[82:83], v89 offset:10240
	ds_read_b64_tr_b16 v[84:85], v89 offset:11264
	s_waitcnt lgkmcnt(4)
	v_mfma_f32_32x32x16_bf16 v[66:81], v[10:13], v[6:9], v[66:81]
	v_fma_f32 v10, v110, v5, v4
	v_exp_f32_e32 v93, v10
	v_fma_f32 v10, v111, v5, v4
	v_exp_f32_e32 v92, v10
	v_exp_f32_e32 v110, v91
	v_add_f32_e32 v105, v107, v108
	ds_read_b64_tr_b16 v[10:11], v109 offset:10304
	ds_read_b64_tr_b16 v[12:13], v109 offset:11328
	s_waitcnt lgkmcnt(4)
	v_mfma_f32_32x32x16_bf16 v[50:65], v[14:17], v[6:9], v[50:65]
	v_fma_f32 v6, v113, v5, v4
	v_exp_f32_e32 v106, v6
	v_cvt_pk_bf16_f32 v6, v87, v90
	v_cvt_pk_bf16_f32 v7, v107, v104
	v_cvt_pk_bf16_f32 v8, v93, v92
	v_cvt_pk_bf16_f32 v9, v110, v106
	v_pk_add_f32 v[14:15], v[104:105], v[102:103]
	s_waitcnt lgkmcnt(2)
	v_mfma_f32_32x32x16_bf16 v[66:81], v[82:85], v[6:9], v[66:81]
	v_add_f32_e64 v90, v14, v14
	v_add_f32_e64 v91, v14, v15
	v_fma_f32 v14, v94, v5, v4
	v_exp_f32_e32 v94, v14
	ds_read_b64_tr_b16 v[14:15], v89 offset:12288
	ds_read_b64_tr_b16 v[16:17], v89 offset:13312
	v_fma_f32 v82, v95, v5, v4
	v_exp_f32_e32 v90, v82
	v_add_f32_e32 v93, v93, v94
	s_waitcnt lgkmcnt(2)
	v_mfma_f32_32x32x16_bf16 v[50:65], v[10:13], v[6:9], v[50:65]
	v_cvt_pk_bf16_f32 v6, v246, v2
	v_cvt_pk_bf16_f32 v7, v247, v98
	v_cvt_pk_bf16_f32 v8, v99, v100
	v_cvt_pk_bf16_f32 v9, v101, v86
	ds_read_b64_tr_b16 v[10:11], v89 offset:14336
	ds_read_b64_tr_b16 v[12:13], v89 offset:15360
	v_pk_add_f32 v[82:83], v[92:93], v[90:91]
	v_fma_f32 v2, v96, v5, v4
	s_waitcnt lgkmcnt(2)
	v_mfma_f32_32x32x16_bf16 v[66:81], v[14:17], v[6:9], v[66:81]
	ds_read_b64_tr_b16 v[14:15], v109 offset:12352
	ds_read_b64_tr_b16 v[16:17], v109 offset:13376
	v_add_f32_e64 v86, v82, v82
	v_add_f32_e64 v87, v82, v83
	v_fmac_f32_e32 v4, v97, v5
	ds_read_b64_tr_b16 v[82:83], v109 offset:14400
	ds_read_b64_tr_b16 v[84:85], v109 offset:15424
	v_exp_f32_e32 v2, v2
	v_exp_f32_e32 v86, v4
	v_cvt_pk_bf16_f32 v4, v248, v88
	s_waitcnt lgkmcnt(2)
	v_mfma_f32_32x32x16_bf16 v[50:65], v[14:17], v[6:9], v[50:65]
	v_cvt_pk_bf16_f32 v5, v108, v102
	v_cvt_pk_bf16_f32 v6, v94, v90
	v_cvt_pk_bf16_f32 v7, v2, v86
	v_add_f32_e32 v107, v110, v2
	v_add_f32_e64 v8, v106, v86
	v_add_f32_e64 v9, v107, v87
	v_add_f32_e32 v2, v8, v9
	v_mfma_f32_32x32x16_bf16 v[66:81], v[10:13], v[4:7], v[66:81]
	v_add_f32_e32 v214, v214, v2
	s_waitcnt lgkmcnt(0)
	v_mfma_f32_32x32x16_bf16 v[50:65], v[82:85], v[4:7], v[50:65]
	s_add_i32 s76, s74, 2
	s_cmp_ge_u32 s76, s51
	s_cbranch_scc0 .LBB0_781

.LBB0_783:
	ds_read_b128 v[226:229], v221
	ds_read_b128 v[230:233], v221 offset:4096
	ds_read_b128 v[234:237], v222
	ds_read_b128 v[238:241], v222 offset:4096
	s_cmp_eq_u32 s72, s74
	s_cselect_b64 s[4:5], -1, 0
	s_cmp_lg_u32 s72, s74
	s_cbranch_scc1 .LBB0_785
	ds_bpermute_b32 v2, v215, v214
	v_mov_b32_e32 v16, v3
	v_mov_b32_e32 v17, v3
	v_mov_b32_e32 v9, v3
	v_mov_b32_e32 v10, v3
	s_waitcnt lgkmcnt(0)
	v_add_f32_e32 v2, v214, v2
	v_div_scale_f32 v4, s[8:9], v2, v2, v197
	v_rcp_f32_e32 v5, v4
	v_div_scale_f32 v6, vcc, v197, v2, v197
	v_mov_b32_e32 v11, v3
	v_fma_f32 v7, -v4, v5, 1.0
	v_fmac_f32_e32 v5, v7, v5
	v_mul_f32_e32 v7, v6, v5
	v_fma_f32 v8, -v4, v7, v6
	v_fmac_f32_e32 v7, v8, v5
	v_fma_f32 v4, -v4, v7, v6
	v_div_fmas_f32 v4, v4, v5, v7
	v_div_fixup_f32 v4, v4, v2, v197
	v_cmp_lt_f32_e32 vcc, 0, v2
	v_mov_b32_e32 v5, v3
	v_mov_b32_e32 v6, v3
	v_cndmask_b32_e32 v2, 0, v4, vcc
	v_pk_fma_f32 v[48:49], v[80:81], v[2:3], v[48:49] op_sel_hi:[1,0,1]
	v_pk_fma_f32 v[46:47], v[78:79], v[2:3], v[46:47] op_sel_hi:[1,0,1]
	v_pk_fma_f32 v[44:45], v[76:77], v[2:3], v[44:45] op_sel_hi:[1,0,1]
	v_pk_fma_f32 v[42:43], v[74:75], v[2:3], v[42:43] op_sel_hi:[1,0,1]
	v_pk_fma_f32 v[40:41], v[72:73], v[2:3], v[40:41] op_sel_hi:[1,0,1]
	v_pk_fma_f32 v[38:39], v[70:71], v[2:3], v[38:39] op_sel_hi:[1,0,1]
	v_pk_fma_f32 v[36:37], v[68:69], v[2:3], v[36:37] op_sel_hi:[1,0,1]
	v_pk_fma_f32 v[34:35], v[66:67], v[2:3], v[34:35] op_sel_hi:[1,0,1]
	v_pk_fma_f32 v[32:33], v[64:65], v[2:3], v[32:33] op_sel_hi:[1,0,1]
	v_pk_fma_f32 v[30:31], v[62:63], v[2:3], v[30:31] op_sel_hi:[1,0,1]
	v_pk_fma_f32 v[28:29], v[60:61], v[2:3], v[28:29] op_sel_hi:[1,0,1]
	v_pk_fma_f32 v[26:27], v[58:59], v[2:3], v[26:27] op_sel_hi:[1,0,1]
	v_pk_fma_f32 v[24:25], v[56:57], v[2:3], v[24:25] op_sel_hi:[1,0,1]
	v_pk_fma_f32 v[22:23], v[54:55], v[2:3], v[22:23] op_sel_hi:[1,0,1]
	v_pk_fma_f32 v[20:21], v[52:53], v[2:3], v[20:21] op_sel_hi:[1,0,1]
	v_pk_fma_f32 v[18:19], v[50:51], v[2:3], v[18:19] op_sel_hi:[1,0,1]
	v_mov_b32_e32 v2, v3
	v_mov_b32_e32 v4, v3
	v_mov_b32_e32 v7, v3
	v_mov_b32_e32 v8, v3
	v_mov_b32_e32 v12, v3
	v_mov_b32_e32 v13, v3
	v_mov_b32_e32 v14, v3
	v_mov_b32_e32 v15, v3
	v_mov_b64_e32 v[64:65], v[16:17]
	v_mov_b64_e32 v[80:81], v[16:17]
	v_mov_b32_e32 v216, 0xff800000
	v_mov_b32_e32 v214, 0
	v_mov_b64_e32 v[62:63], v[14:15]
	v_mov_b64_e32 v[60:61], v[12:13]
	v_mov_b64_e32 v[58:59], v[10:11]
	v_mov_b64_e32 v[56:57], v[8:9]
	v_mov_b64_e32 v[54:55], v[6:7]
	v_mov_b64_e32 v[52:53], v[4:5]
	v_mov_b64_e32 v[50:51], v[2:3]
	v_mov_b64_e32 v[78:79], v[14:15]
	v_mov_b64_e32 v[76:77], v[12:13]
	v_mov_b64_e32 v[74:75], v[10:11]
	v_mov_b64_e32 v[72:73], v[8:9]
	v_mov_b64_e32 v[70:71], v[6:7]
	v_mov_b64_e32 v[68:69], v[4:5]
	v_mov_b64_e32 v[66:67], v[2:3]

; #define LAS __attribute__((address_space(3)))
; #define MFMA32(a, b, c) __builtin_amdgcn_mfma_f32_32x32x16_bf16((a), (b), (c), 0, 0, 0)
; DI float fexp2(float x) { return __builtin_amdgcn_exp2f(x); }
; DI float half_max(float v) { return fmaxf(v, __shfl_xor(v, 32)); }
; DI void flash_qk(const LAS unsigned char* kb, const bf16x8 (&qf)[4], f32x16& p0, f32x16& p1, int r32, int h) {
;     ...
;     for (int s = 0; s < 4; ++s) {
;         const int off = r32 * 128 + (((2 * s + h) ^ sw) << 4);
;         const bf16x8 a0 = *(const LAS bf16x8*)(kb + off), a1 = *(const LAS bf16x8*)(kb + off + 4096);
;         p0 = MFMA32(a0, qf[s], p0); p1 = MFMA32(a1, qf[s], p1);
;     }
; DI void flash_pv(FState& st, f32x16& p0, f32x16& p1, bool rowon, const LAS unsigned char* vb, int lane) {
;     float mx = fmaxf(p0[0], p1[0]);
; #pragma unroll
;     for (int r = 1; r < 16; ++r) asm("v_max3_f32 %0, %1, %2, %3" : "=v"(mx) : "v"(mx), "v"(p0[r]), "v"(p1[r]));
;     mx = half_max(mx);
;     mx = rowon ? mx : NINF;
;     const bool upd = mx > st.m + THR_RAW;
;     if (__any(upd)) {
;         const float mn = upd ? mx : st.m;
;         const float alpha = upd ? fexp2((st.m - mn) * SM_C) : 1.0f;
;         st.m = mn; st.l *= alpha;
; #pragma unroll
;         for (int r = 0; r < 16; ++r) { st.o0[r] *= alpha; st.o1[r] *= alpha; }
;     }
.LBB0_793:
	v_max_f32_e32 v2, v82, v82
	v_max_f32_e32 v4, v98, v98
	v_max_f32_e32 v2, v4, v2
	v_max3_f32 v2, v2, v99, v83
	s_waitcnt lgkmcnt(3)
	v_mfma_f32_32x32x16_bf16 v[130:145], v[226:229], v[146:149], 0
	v_max3_f32 v2, v2, v100, v84
	v_max3_f32 v2, v2, v101, v85
	v_max3_f32 v2, v2, v102, v86
	v_max3_f32 v2, v2, v103, v87
	v_max3_f32 v2, v2, v104, v88
	s_waitcnt lgkmcnt(2)
	v_mfma_f32_32x32x16_bf16 v[114:129], v[230:233], v[146:149], 0
	ds_read_b128 v[226:229], v223
	ds_read_b128 v[230:233], v223 offset:4096
	v_max3_f32 v2, v2, v105, v89
	v_max3_f32 v2, v2, v106, v90
	v_max3_f32 v2, v2, v107, v91
	v_max3_f32 v2, v2, v108, v92
	v_max3_f32 v2, v2, v109, v93
	s_waitcnt lgkmcnt(3)
	v_mfma_f32_32x32x16_bf16 v[130:145], v[234:237], v[150:153], v[130:145]
	v_max3_f32 v2, v2, v110, v94
	v_max3_f32 v2, v2, v111, v95
	v_max3_f32 v2, v2, v112, v96
	v_max3_f32 v2, v2, v113, v97
	v_mov_b32_e32 v4, v2
	s_nop 1
	v_permlane32_swap_b32_e32 v4, v2
	s_nop 0
	v_max_f32_e32 v2, v2, v4
	v_cndmask_b32_e64 v2, v186, v2, s[8:9]
	v_add_f32_e32 v4, 0x42317218, v216
	v_cmp_gt_f32_e32 vcc, v2, v4
	s_cbranch_vccz .LBB0_795
	s_nop 0
	v_cndmask_b32_e32 v4, v216, v2, vcc
	v_sub_f32_e32 v2, v216, v4
	v_mul_f32_e32 v2, 0x3e38aa3b, v2
	v_exp_f32_e32 v2, v2
	v_mov_b32_e32 v216, v4
	v_cndmask_b32_e32 v2, 1.0, v2, vcc
	v_mul_f32_e32 v214, v214, v2
	v_pk_mul_f32 v[80:81], v[80:81], v[2:3] op_sel_hi:[1,0]
	v_pk_mul_f32 v[78:79], v[78:79], v[2:3] op_sel_hi:[1,0]
	v_pk_mul_f32 v[76:77], v[76:77], v[2:3] op_sel_hi:[1,0]
	v_pk_mul_f32 v[74:75], v[74:75], v[2:3] op_sel_hi:[1,0]
	v_pk_mul_f32 v[72:73], v[72:73], v[2:3] op_sel_hi:[1,0]
	v_pk_mul_f32 v[70:71], v[70:71], v[2:3] op_sel_hi:[1,0]
	v_pk_mul_f32 v[68:69], v[68:69], v[2:3] op_sel_hi:[1,0]
	v_pk_mul_f32 v[66:67], v[66:67], v[2:3] op_sel_hi:[1,0]
	v_pk_mul_f32 v[64:65], v[64:65], v[2:3] op_sel_hi:[1,0]
	v_pk_mul_f32 v[62:63], v[62:63], v[2:3] op_sel_hi:[1,0]
	v_pk_mul_f32 v[60:61], v[60:61], v[2:3] op_sel_hi:[1,0]
	v_pk_mul_f32 v[58:59], v[58:59], v[2:3] op_sel_hi:[1,0]
	v_pk_mul_f32 v[56:57], v[56:57], v[2:3] op_sel_hi:[1,0]
	v_pk_mul_f32 v[54:55], v[54:55], v[2:3] op_sel_hi:[1,0]
	v_pk_mul_f32 v[52:53], v[52:53], v[2:3] op_sel_hi:[1,0]
	v_pk_mul_f32 v[50:51], v[50:51], v[2:3] op_sel_hi:[1,0]

; #define LAS __attribute__((address_space(3)))
; #define MFMA32(a, b, c) __builtin_amdgcn_mfma_f32_32x32x16_bf16((a), (b), (c), 0, 0, 0)
; DI float fexp2(float x) { return __builtin_amdgcn_exp2f(x); }
; DI s16x4 vtr(const LAS unsigned char* p) { return __builtin_bit_cast(s16x4, __builtin_amdgcn_ds_read_tr16_b64_v4i16((LAS v4i16_t*)p)); }
; DI void flash_pv(FState& st, f32x16& p0, f32x16& p1, bool rowon, const LAS unsigned char* vb, int lane) {
;     ...
;     const float cl = rowon ? SM_C : 0.0f;
;     const float bl = rowon ? ((st.m == NINF) ? 0.0f : -st.m * SM_C) : NINF;
;     float sum = 0.f;
; #pragma unroll
;     for (int r = 0; r < 16; ++r) { p0[r] = fexp2(__builtin_fmaf(p0[r], cl, bl)); p1[r] = fexp2(__builtin_fmaf(p1[r], cl, bl)); sum += p0[r] + p1[r]; }
;     st.l += sum;
;     const int h = lane >> 5;
;     const int vx = (((lane & 15) >> 3) & 1) * 64;
;     const LAS unsigned char* vp = vb + (4 * h + ((lane & 15) >> 2)) * 128 + ((lane >> 4) & 1) * 32 + (lane & 3) * 8;
; #pragma unroll
;     for (int sub = 0; sub < 2; ++sub)
; #pragma unroll
;         for (int s2 = 0; s2 < 2; ++s2) {
;             const bf16x8 pf = pack8h(sub ? p1 : p0, s2);
;             const LAS unsigned char* vq = vp + (32 * sub + 16 * s2) * 128;
;             { const s16x4 lo = vtr(vq + vx), hi = vtr(vq + 1024 + vx); const bf16x8 vf = {lo[0], lo[1], lo[2], lo[3], hi[0], hi[1], hi[2], hi[3]}; st.o0 = MFMA32(vf, pf, st.o0); }
;             { const s16x4 lo = vtr(vq + (64 - vx)), hi = vtr(vq + 1024 + (64 - vx)); const bf16x8 vf = {lo[0], lo[1], lo[2], lo[3], hi[0], hi[1], hi[2], hi[3]}; st.o1 = MFMA32(vf, pf, st.o1); }
;         }
; DI void nsa_task(LAS unsigned char* lds, const bf16_t* Z, const unsigned* selm, const bf16_t* OCMP, bf16_t* YA, int b, int hk, int c, int tid, int wave, int lane) {
;     ...
;     for (int it0 = 0; it0 < ntot; it0 += 3) {
;         NSA_STEP(it0, kA, vA);
;         if (it0 + 1 < ntot) NSA_STEP(it0 + 1, kB, vB);
;         if (it0 + 2 < ntot) NSA_STEP(it0 + 2, kC, vC);
;     }
.LBB0_799:
	s_or_b64 exec, exec, s[4:5]
	s_waitcnt lgkmcnt(2)
	v_mfma_f32_32x32x16_bf16 v[114:129], v[238:241], v[150:153], v[114:129]
	ds_read_b128 v[234:237], v224
	ds_read_b128 v[238:241], v224 offset:4096
	v_fma_f32 v2, v98, v5, v4
	v_exp_f32_e32 v246, v2
	v_fma_f32 v2, v82, v5, v4
	v_exp_f32_e32 v247, v2
	v_fma_f32 v2, v99, v5, v4
	v_exp_f32_e32 v10, v2
	v_fma_f32 v2, v83, v5, v4
	v_exp_f32_e32 v2, v2
	v_add_f32_e32 v11, v246, v247
	v_pk_add_f32 v[6:7], v[10:11], v[2:3]
	s_waitcnt lgkmcnt(3)
	v_mfma_f32_32x32x16_bf16 v[130:145], v[226:229], v[154:157], v[130:145]
	s_nop 0
	v_pk_add_f32 v[98:99], v[6:7], v[6:7] op_sel_hi:[0,1]
	v_fma_f32 v6, v100, v5, v4
	v_exp_f32_e32 v11, v6
	v_fma_f32 v6, v84, v5, v4
	v_exp_f32_e32 v248, v6
	v_fma_f32 v6, v101, v5, v4
	v_exp_f32_e32 v12, v6
	v_fma_f32 v6, v85, v5, v4
	v_exp_f32_e32 v98, v6
	s_waitcnt lgkmcnt(2)
	v_mfma_f32_32x32x16_bf16 v[114:129], v[230:233], v[154:157], v[114:129]
	v_add_f32_e32 v13, v11, v248
	v_cvt_pk_bf16_f32 v10, v246, v10
	v_cvt_pk_bf16_f32 v11, v11, v12
	v_pk_add_f32 v[6:7], v[12:13], v[98:99]
	s_nop 0
	v_pk_add_f32 v[100:101], v[6:7], v[6:7] op_sel_hi:[0,1]
	v_fma_f32 v6, v102, v5, v4
	v_exp_f32_e32 v13, v6
	v_fma_f32 v6, v86, v5, v4
	v_exp_f32_e32 v99, v6
	s_waitcnt lgkmcnt(1)
	v_mfma_f32_32x32x16_bf16 v[130:145], v[234:237], v[158:161], v[130:145]
	v_fma_f32 v6, v103, v5, v4
	v_exp_f32_e32 v14, v6
	v_fma_f32 v6, v87, v5, v4
	v_exp_f32_e32 v100, v6
	v_add_f32_e32 v15, v13, v99
	v_cvt_pk_bf16_f32 v12, v13, v14
	v_pk_add_f32 v[6:7], v[14:15], v[100:101]
	s_nop 0
	v_pk_add_f32 v[86:87], v[6:7], v[6:7] op_sel_hi:[0,1]
	v_fma_f32 v6, v104, v5, v4
	s_waitcnt lgkmcnt(0)
	v_mfma_f32_32x32x16_bf16 v[114:129], v[238:241], v[158:161], v[114:129]
	v_exp_f32_e32 v15, v6
	v_fma_f32 v6, v88, v5, v4
	v_exp_f32_e32 v101, v6
	v_fma_f32 v6, v105, v5, v4
	v_exp_f32_e32 v16, v6
	v_fma_f32 v6, v89, v5, v4
	v_exp_f32_e32 v86, v6
	v_add_f32_e32 v17, v15, v101
	v_cvt_pk_bf16_f32 v13, v15, v16
	v_pk_add_f32 v[6:7], v[16:17], v[86:87]
	s_nop 0
	v_pk_add_f32 v[88:89], v[6:7], v[6:7] op_sel_hi:[0,1]
	v_fma_f32 v6, v106, v5, v4
	v_exp_f32_e32 v87, v6
	v_fma_f32 v6, v90, v5, v4
	v_exp_f32_e32 v249, v6
	v_fma_f32 v6, v107, v5, v4
	v_exp_f32_e32 v90, v6
	v_fma_f32 v6, v91, v5, v4
	v_exp_f32_e32 v88, v6
	v_fma_f32 v6, v108, v5, v4
	v_exp_f32_e32 v107, v6
	v_fma_f32 v6, v92, v5, v4
	v_add_f32_e32 v91, v87, v249
	v_exp_f32_e32 v108, v6
	v_pk_add_f32 v[6:7], v[90:91], v[88:89]
	v_fma_f32 v91, v112, v5, v4
	v_pk_add_f32 v[102:103], v[6:7], v[6:7] op_sel_hi:[0,1]
	v_fma_f32 v6, v109, v5, v4
	v_exp_f32_e32 v104, v6
	v_fma_f32 v6, v93, v5, v4
	v_exp_f32_e32 v102, v6
	ds_read_b64_tr_b16 v[6:7], v218 offset:40960
	ds_read_b64_tr_b16 v[8:9], v218 offset:41984
	ds_read_b64_tr_b16 v[14:15], v217 offset:41024
	ds_read_b64_tr_b16 v[16:17], v217 offset:42048
	ds_read_b64_tr_b16 v[82:83], v218 offset:43008
	ds_read_b64_tr_b16 v[84:85], v218 offset:44032
	s_waitcnt lgkmcnt(4)
	v_mfma_f32_32x32x16_bf16 v[66:81], v[6:9], v[10:13], v[66:81]
	v_fma_f32 v6, v110, v5, v4
	v_exp_f32_e32 v89, v6
	v_fma_f32 v6, v111, v5, v4
	v_exp_f32_e32 v92, v6
	v_exp_f32_e32 v109, v91
	v_add_f32_e32 v105, v107, v108
	ds_read_b64_tr_b16 v[6:7], v217 offset:43072
	ds_read_b64_tr_b16 v[8:9], v217 offset:44096
	s_waitcnt lgkmcnt(4)
	v_mfma_f32_32x32x16_bf16 v[50:65], v[14:17], v[10:13], v[50:65]
	v_fma_f32 v10, v113, v5, v4
	v_exp_f32_e32 v106, v10
	v_cvt_pk_bf16_f32 v10, v87, v90
	v_cvt_pk_bf16_f32 v11, v107, v104
	v_cvt_pk_bf16_f32 v12, v89, v92
	v_cvt_pk_bf16_f32 v13, v109, v106
	v_pk_add_f32 v[14:15], v[104:105], v[102:103]
	s_waitcnt lgkmcnt(2)
	v_mfma_f32_32x32x16_bf16 v[66:81], v[82:85], v[10:13], v[66:81]
	v_add_f32_e64 v90, v14, v14
	v_add_f32_e64 v91, v14, v15
	v_fma_f32 v14, v94, v5, v4
	v_exp_f32_e32 v94, v14
	ds_read_b64_tr_b16 v[14:15], v218 offset:45056
	ds_read_b64_tr_b16 v[16:17], v218 offset:46080
	v_fma_f32 v82, v95, v5, v4
	v_exp_f32_e32 v90, v82
	v_add_f32_e32 v93, v89, v94
	s_waitcnt lgkmcnt(2)
	v_mfma_f32_32x32x16_bf16 v[50:65], v[6:9], v[10:13], v[50:65]
	v_cvt_pk_bf16_f32 v6, v247, v2
	v_cvt_pk_bf16_f32 v7, v248, v98
	v_cvt_pk_bf16_f32 v8, v99, v100
	v_cvt_pk_bf16_f32 v9, v101, v86
	ds_read_b64_tr_b16 v[10:11], v218 offset:47104
	ds_read_b64_tr_b16 v[12:13], v218 offset:48128
	v_pk_add_f32 v[82:83], v[92:93], v[90:91]
	v_fma_f32 v2, v96, v5, v4
	s_waitcnt lgkmcnt(2)
	v_mfma_f32_32x32x16_bf16 v[66:81], v[14:17], v[6:9], v[66:81]
	ds_read_b64_tr_b16 v[14:15], v217 offset:45120
	ds_read_b64_tr_b16 v[16:17], v217 offset:46144
	v_add_f32_e64 v86, v82, v82
	v_add_f32_e64 v87, v82, v83
	v_fmac_f32_e32 v4, v97, v5
	ds_read_b64_tr_b16 v[82:83], v217 offset:47168
	ds_read_b64_tr_b16 v[84:85], v217 offset:48192
	v_exp_f32_e32 v2, v2
	v_exp_f32_e32 v86, v4
	v_cvt_pk_bf16_f32 v4, v249, v88
	s_waitcnt lgkmcnt(2)
	v_mfma_f32_32x32x16_bf16 v[50:65], v[14:17], v[6:9], v[50:65]
	v_cvt_pk_bf16_f32 v5, v108, v102
	v_cvt_pk_bf16_f32 v6, v94, v90
	v_cvt_pk_bf16_f32 v7, v2, v86
	v_add_f32_e32 v107, v109, v2
	v_add_f32_e64 v8, v106, v86
	v_add_f32_e64 v9, v107, v87
	v_add_f32_e32 v2, v8, v9
	v_mfma_f32_32x32x16_bf16 v[66:81], v[10:13], v[4:7], v[66:81]
	v_add_f32_e32 v214, v214, v2
	s_waitcnt lgkmcnt(0)
	v_mfma_f32_32x32x16_bf16 v[50:65], v[82:85], v[4:7], v[50:65]
	s_add_i32 s52, s52, -3
	s_andn2_b64 vcc, exec, s[6:7]
	s_add_i32 s53, s53, 0xc000
	s_cbranch_vccz .LBB0_712
